# norm phases: prompt-row rstd block split - its SSP loads are issued before the sample-row loop and the sqrt/div/store finish runs after it, so workgroups 0-31 no longer serialize both parts (4 sites,
# baseline (speedup 1.0000x reference)
; template <int MODE>
; DI void norm_phase(const Args& a, const Frame& F, int nslab, float sscale, float* RSTD, const float* SSP) {
;     ...
;         for (int row = F.bid * NTHR + F.tid; row < NP; row += F.G * NTHR) { const f32x4* q = (const f32x4*)(SSP + (size_t)row * 16); const f32x4 p = (q[0] + q[1]) + (q[2] + q[3]);
;             RSTD[row] = 1.f / sqrtf(((p[0] + p[1]) + (p[2] + p[3])) * (1.f / DM) + EPS); }
.LBB0_214:
	v_mov_b64_e32 v[244:245], v[6:7]
	global_load_dwordx4 v[228:231], v[8:9], off
	global_load_dwordx4 v[232:235], v[8:9], off offset:16
	global_load_dwordx4 v[236:239], v[8:9], off offset:32
	global_load_dwordx4 v[240:243], v[8:9], off offset:48

; template <int MODE>
; DI void norm_phase(const Args& a, const Frame& F, int nslab, float sscale, float* RSTD, const float* SSP) {
;     ...
;         for (int row = F.bid * NTHR + F.tid; row < NP; row += F.G * NTHR) { const f32x4* q = (const f32x4*)(SSP + (size_t)row * 16); const f32x4 p = (q[0] + q[1]) + (q[2] + q[3]);
;             RSTD[row] = 1.f / sqrtf(((p[0] + p[1]) + (p[2] + p[3])) * (1.f / DM) + EPS); }
.Lnp_B_0:
	s_movk_i32 s2, 0x4000
	v_lshl_add_u32 v4, s69, 9, v0
	v_cmp_gt_i32_e32 vcc, s2, v4
	s_and_saveexec_b64 s[100:101], vcc
	s_cbranch_execz .Lnp_F_0
	s_waitcnt vmcnt(0)
	v_mov_b64_e32 v[10:11], v[228:229]
	v_mov_b64_e32 v[12:13], v[230:231]
	v_mov_b64_e32 v[14:15], v[232:233]
	v_mov_b64_e32 v[16:17], v[234:235]
	v_mov_b64_e32 v[18:19], v[236:237]
	v_mov_b64_e32 v[20:21], v[238:239]
	v_mov_b64_e32 v[22:23], v[240:241]
	v_mov_b64_e32 v[24:25], v[242:243]
	v_pk_add_f32 v[12:13], v[12:13], v[16:17]
	v_pk_add_f32 v[10:11], v[10:11], v[14:15]
	v_pk_add_f32 v[14:15], v[20:21], v[24:25]
	v_pk_add_f32 v[16:17], v[18:19], v[22:23]
	v_pk_add_f32 v[12:13], v[12:13], v[14:15]
	v_pk_add_f32 v[10:11], v[10:11], v[16:17]
	s_nop 0
	v_pk_mov_b32 v[14:15], v[10:11], v[12:13] op_sel:[1,0]
	v_mov_b32_e32 v11, v13
	v_pk_add_f32 v[10:11], v[14:15], v[10:11]
	s_nop 0
	v_add_f32_e32 v3, v10, v11
	v_fmamk_f32 v3, v3, 0x3a800000, v1
	v_mul_f32_e32 v5, 0x4f800000, v3
	v_cmp_gt_f32_e32 vcc, s67, v3
	s_nop 1
	v_cndmask_b32_e32 v3, v3, v5, vcc
	v_sqrt_f32_e32 v5, v3
	s_nop 0
	v_add_u32_e32 v10, -1, v5
	v_add_u32_e32 v11, 1, v5
	v_fma_f32 v12, -v10, v5, v3
	v_fma_f32 v13, -v11, v5, v3
	v_cmp_ge_f32_e64 s[2:3], 0, v12
	s_nop 1
	v_cndmask_b32_e64 v5, v5, v10, s[2:3]
	v_cmp_lt_f32_e64 s[2:3], 0, v13
	s_nop 1
	v_cndmask_b32_e64 v5, v5, v11, s[2:3]
	v_mul_f32_e32 v10, 0x37800000, v5
	v_cndmask_b32_e32 v5, v5, v10, vcc
	v_cmp_class_f32_e32 vcc, v3, v196
	s_nop 1
	v_cndmask_b32_e32 v3, v5, v3, vcc
	v_div_scale_f32 v5, s[2:3], v3, v3, 1.0
	v_rcp_f32_e32 v10, v5
	v_div_scale_f32 v11, vcc, 1.0, v3, 1.0
	v_fma_f32 v12, -v5, v10, 1.0
	v_fmac_f32_e32 v10, v12, v10
	v_mul_f32_e32 v12, v11, v10
	v_fma_f32 v13, -v5, v12, v11
	v_fmac_f32_e32 v12, v13, v10
	v_fma_f32 v5, -v5, v12, v11
	v_div_fmas_f32 v5, v5, v10, v12
	v_div_fixup_f32 v3, v5, v3, 1.0
	global_store_dword v[244:245], v3, off
.Lnp_F_0:
	s_or_b64 exec, exec, s[100:101]
